# FF1 phase: first K-loop iteration of units 2-4 peeled; its first two counted waits exclude the previous unit's 16 epilogue stores (vmcnt(24)), so the stores drain beside one K-tile of MFMAs
# speedup vs baseline: 1.0582x; 1.0486x over previous
.LBB0_854:
	v_mov_b32_e32 v123, 0
	s_andn2_b64 vcc, exec, s[46:47]
	v_mov_b32_e32 v122, v123
	v_mov_b32_e32 v121, v123
	v_mov_b32_e32 v120, v123
	v_mov_b32_e32 v127, v123
	v_mov_b32_e32 v126, v123
	v_mov_b32_e32 v125, v123
	v_mov_b32_e32 v124, v123
	v_mov_b32_e32 v111, v123
	v_mov_b32_e32 v110, v123
	v_mov_b32_e32 v109, v123
	v_mov_b32_e32 v108, v123
	v_mov_b32_e32 v107, v123
	v_mov_b32_e32 v106, v123
	v_mov_b32_e32 v105, v123
	v_mov_b32_e32 v104, v123
	v_mov_b32_e32 v95, v123
	v_mov_b32_e32 v94, v123
	v_mov_b32_e32 v93, v123
	v_mov_b32_e32 v92, v123
	v_mov_b32_e32 v91, v123
	v_mov_b32_e32 v90, v123
	v_mov_b32_e32 v89, v123
	v_mov_b32_e32 v88, v123
	v_mov_b32_e32 v79, v123
	v_mov_b32_e32 v78, v123
	v_mov_b32_e32 v77, v123
	v_mov_b32_e32 v76, v123
	v_mov_b32_e32 v75, v123
	v_mov_b32_e32 v74, v123
	v_mov_b32_e32 v73, v123
	v_mov_b32_e32 v72, v123
	v_mov_b32_e32 v119, v123
	v_mov_b32_e32 v118, v123
	v_mov_b32_e32 v117, v123
	v_mov_b32_e32 v116, v123
	v_mov_b32_e32 v115, v123
	v_mov_b32_e32 v114, v123
	v_mov_b32_e32 v113, v123
	v_mov_b32_e32 v112, v123
	v_mov_b32_e32 v103, v123
	v_mov_b32_e32 v102, v123
	v_mov_b32_e32 v101, v123
	v_mov_b32_e32 v100, v123
	v_mov_b32_e32 v99, v123
	v_mov_b32_e32 v98, v123
	v_mov_b32_e32 v97, v123
	v_mov_b32_e32 v96, v123
	v_mov_b32_e32 v87, v123
	v_mov_b32_e32 v86, v123
	v_mov_b32_e32 v85, v123
	v_mov_b32_e32 v84, v123
	v_mov_b32_e32 v83, v123
	v_mov_b32_e32 v82, v123
	v_mov_b32_e32 v81, v123
	v_mov_b32_e32 v80, v123
	v_mov_b32_e32 v71, v123
	v_mov_b32_e32 v70, v123
	v_mov_b32_e32 v69, v123
	v_mov_b32_e32 v68, v123
	v_mov_b32_e32 v67, v123
	v_mov_b32_e32 v66, v123
	v_mov_b32_e32 v65, v123
	v_mov_b32_e32 v64, v123
	v_mov_b32_e32 v63, v123
	v_mov_b32_e32 v62, v123
	v_mov_b32_e32 v61, v123
	v_mov_b32_e32 v60, v123
	v_mov_b32_e32 v59, v123
	v_mov_b32_e32 v58, v123
	v_mov_b32_e32 v57, v123
	v_mov_b32_e32 v56, v123
	v_mov_b32_e32 v47, v123
	v_mov_b32_e32 v46, v123
	v_mov_b32_e32 v45, v123
	v_mov_b32_e32 v44, v123
	v_mov_b32_e32 v43, v123
	v_mov_b32_e32 v42, v123
	v_mov_b32_e32 v41, v123
	v_mov_b32_e32 v40, v123
	v_mov_b32_e32 v31, v123
	v_mov_b32_e32 v30, v123
	v_mov_b32_e32 v29, v123
	v_mov_b32_e32 v28, v123
	v_mov_b32_e32 v27, v123
	v_mov_b32_e32 v26, v123
	v_mov_b32_e32 v25, v123
	v_mov_b32_e32 v24, v123
	v_mov_b32_e32 v15, v123
	v_mov_b32_e32 v14, v123
	v_mov_b32_e32 v13, v123
	v_mov_b32_e32 v12, v123
	v_mov_b32_e32 v11, v123
	v_mov_b32_e32 v10, v123
	v_mov_b32_e32 v9, v123
	v_mov_b32_e32 v8, v123
	v_mov_b32_e32 v55, v123
	v_mov_b32_e32 v54, v123
	v_mov_b32_e32 v53, v123
	v_mov_b32_e32 v52, v123
	v_mov_b32_e32 v51, v123
	v_mov_b32_e32 v50, v123
	v_mov_b32_e32 v49, v123
	v_mov_b32_e32 v48, v123
	v_mov_b32_e32 v39, v123
	v_mov_b32_e32 v38, v123
	v_mov_b32_e32 v37, v123
	v_mov_b32_e32 v36, v123
	v_mov_b32_e32 v35, v123
	v_mov_b32_e32 v34, v123
	v_mov_b32_e32 v33, v123
	v_mov_b32_e32 v32, v123
	v_mov_b32_e32 v23, v123
	v_mov_b32_e32 v22, v123
	v_mov_b32_e32 v21, v123
	v_mov_b32_e32 v20, v123
	v_mov_b32_e32 v19, v123
	v_mov_b32_e32 v18, v123
	v_mov_b32_e32 v17, v123
	v_mov_b32_e32 v16, v123
	v_mov_b32_e32 v7, v123
	v_mov_b32_e32 v6, v123
	v_mov_b32_e32 v5, v123
	v_mov_b32_e32 v4, v123
	v_mov_b32_e32 v3, v123
	v_mov_b32_e32 v2, v123
	v_mov_b32_e32 v1, v123
	v_mov_b32_e32 v0, v123
	s_cbranch_vccnz .LBB0_857
	s_add_u32 s60, s60, 0x80
	s_addc_u32 s61, s61, 0
	s_add_u32 s82, s62, 0x100
	v_mov_b32_e32 v0, 0
	s_addc_u32 s83, s63, 0
	s_mov_b32 s62, 0
	v_mov_b32_e32 v1, v0
	v_mov_b32_e32 v2, v0
	v_mov_b32_e32 v3, v0
	v_mov_b32_e32 v4, v0
	v_mov_b32_e32 v5, v0
	v_mov_b32_e32 v6, v0
	v_mov_b32_e32 v7, v0
	v_mov_b32_e32 v16, v0
	v_mov_b32_e32 v17, v0
	v_mov_b32_e32 v18, v0
	v_mov_b32_e32 v19, v0
	v_mov_b32_e32 v20, v0
	v_mov_b32_e32 v21, v0
	v_mov_b32_e32 v22, v0
	v_mov_b32_e32 v23, v0
	v_mov_b32_e32 v32, v0
	v_mov_b32_e32 v33, v0
	v_mov_b32_e32 v34, v0
	v_mov_b32_e32 v35, v0
	v_mov_b32_e32 v36, v0
	v_mov_b32_e32 v37, v0
	v_mov_b32_e32 v38, v0
	v_mov_b32_e32 v39, v0
	v_mov_b32_e32 v48, v0
	v_mov_b32_e32 v49, v0
	v_mov_b32_e32 v50, v0
	v_mov_b32_e32 v51, v0
	v_mov_b32_e32 v52, v0
	v_mov_b32_e32 v53, v0
	v_mov_b32_e32 v54, v0
	v_mov_b32_e32 v55, v0
	v_mov_b32_e32 v8, v0
	v_mov_b32_e32 v9, v0
	v_mov_b32_e32 v10, v0
	v_mov_b32_e32 v11, v0
	v_mov_b32_e32 v12, v0
	v_mov_b32_e32 v13, v0
	v_mov_b32_e32 v14, v0
	v_mov_b32_e32 v15, v0
	v_mov_b32_e32 v24, v0
	v_mov_b32_e32 v25, v0
	v_mov_b32_e32 v26, v0
	v_mov_b32_e32 v27, v0
	v_mov_b32_e32 v28, v0
	v_mov_b32_e32 v29, v0
	v_mov_b32_e32 v30, v0
	v_mov_b32_e32 v31, v0
	v_mov_b32_e32 v40, v0
	v_mov_b32_e32 v41, v0
	v_mov_b32_e32 v42, v0
	v_mov_b32_e32 v43, v0
	v_mov_b32_e32 v44, v0
	v_mov_b32_e32 v45, v0
	v_mov_b32_e32 v46, v0
	v_mov_b32_e32 v47, v0
	v_mov_b32_e32 v56, v0
	v_mov_b32_e32 v57, v0
	v_mov_b32_e32 v58, v0
	v_mov_b32_e32 v59, v0
	v_mov_b32_e32 v60, v0
	v_mov_b32_e32 v61, v0
	v_mov_b32_e32 v62, v0
	v_mov_b32_e32 v63, v0
	v_mov_b32_e32 v64, v0
	v_mov_b32_e32 v65, v0
	v_mov_b32_e32 v66, v0
	v_mov_b32_e32 v67, v0
	v_mov_b32_e32 v68, v0
	v_mov_b32_e32 v69, v0
	v_mov_b32_e32 v70, v0
	v_mov_b32_e32 v71, v0
	v_mov_b32_e32 v80, v0
	v_mov_b32_e32 v81, v0
	v_mov_b32_e32 v82, v0
	v_mov_b32_e32 v83, v0
	v_mov_b32_e32 v84, v0
	v_mov_b32_e32 v85, v0
	v_mov_b32_e32 v86, v0
	v_mov_b32_e32 v87, v0
	v_mov_b32_e32 v96, v0
	v_mov_b32_e32 v97, v0
	v_mov_b32_e32 v98, v0
	v_mov_b32_e32 v99, v0
	v_mov_b32_e32 v100, v0
	v_mov_b32_e32 v101, v0
	v_mov_b32_e32 v102, v0
	v_mov_b32_e32 v103, v0
	v_mov_b32_e32 v112, v0
	v_mov_b32_e32 v113, v0
	v_mov_b32_e32 v114, v0
	v_mov_b32_e32 v115, v0
	v_mov_b32_e32 v116, v0
	v_mov_b32_e32 v117, v0
	v_mov_b32_e32 v118, v0
	v_mov_b32_e32 v119, v0
	v_mov_b32_e32 v72, v0
	v_mov_b32_e32 v73, v0
	v_mov_b32_e32 v74, v0
	v_mov_b32_e32 v75, v0
	v_mov_b32_e32 v76, v0
	v_mov_b32_e32 v77, v0
	v_mov_b32_e32 v78, v0
	v_mov_b32_e32 v79, v0
	v_mov_b32_e32 v88, v0
	v_mov_b32_e32 v89, v0
	v_mov_b32_e32 v90, v0
	v_mov_b32_e32 v91, v0
	v_mov_b32_e32 v92, v0
	v_mov_b32_e32 v93, v0
	v_mov_b32_e32 v94, v0
	v_mov_b32_e32 v95, v0
	v_mov_b32_e32 v104, v0
	v_mov_b32_e32 v105, v0
	v_mov_b32_e32 v106, v0
	v_mov_b32_e32 v107, v0
	v_mov_b32_e32 v108, v0
	v_mov_b32_e32 v109, v0
	v_mov_b32_e32 v110, v0
	v_mov_b32_e32 v111, v0
	v_mov_b32_e32 v124, v0
	v_mov_b32_e32 v125, v0
	v_mov_b32_e32 v126, v0
	v_mov_b32_e32 v127, v0
	v_mov_b32_e32 v120, v0
	v_mov_b32_e32 v121, v0
	v_mov_b32_e32 v122, v0
	v_mov_b32_e32 v123, v0
	s_cmp_eq_u32 s29, 1
	s_cbranch_scc1 .LBB0_856
	ds_read_b128 v[152:155], v149
	ds_read_b128 v[156:159], v149 offset:1024
	ds_read_b128 v[160:163], v149 offset:2048
	ds_read_b128 v[164:167], v149 offset:3072
	ds_read_b128 v[168:171], v150
	ds_read_b128 v[172:175], v150 offset:1024
	ds_read_b128 v[176:179], v150 offset:2048
	ds_read_b128 v[180:183], v150 offset:3072
	s_add_i32 s84, s62, 2
	s_add_u32 s85, s60, 0x80
	s_addc_u32 s63, s61, 0
	s_cmp_eq_u32 s65, s62
	s_cselect_b32 s62, s10, s85
	s_cselect_b32 s63, s11, s63
	s_cselect_b32 s87, s59, s83
	s_cselect_b32 s86, s58, s82
	v_lshl_add_u64 v[144:145], s[60:61], 0, v[136:137]
	s_add_i32 m0, s25, 0xc000
	ds_read_b128 v[184:187], v151
	ds_read_b128 v[188:191], v151 offset:1024
	ds_read_b128 v[192:195], v151 offset:2048
	ds_read_b128 v[196:199], v151 offset:3072
	ds_read_b128 v[200:203], v151 offset:4096
	ds_read_b128 v[204:207], v151 offset:5120
	ds_read_b128 v[208:211], v151 offset:6144
	ds_read_b128 v[212:215], v151 offset:7168
	global_load_lds_dwordx4 v[144:145], off
	v_lshl_add_u64 v[144:145], s[60:61], 0, v[138:139]
	s_add_i32 m0, s25, 0xe000
	s_nop 0
	global_load_lds_dwordx4 v[144:145], off
	s_waitcnt vmcnt(24)
	s_waitcnt lgkmcnt(0)
	s_barrier
	s_setprio 1
	s_waitcnt lgkmcnt(0)
	v_mfma_f32_16x16x32_bf16 v[120:123], v[152:155], v[184:187], v[120:123]
	v_mfma_f32_16x16x32_bf16 v[124:127], v[160:163], v[184:187], v[124:127]
	v_mfma_f32_16x16x32_bf16 v[108:111], v[152:155], v[192:195], v[108:111]
	v_mfma_f32_16x16x32_bf16 v[104:107], v[160:163], v[192:195], v[104:107]
	v_mfma_f32_16x16x32_bf16 v[92:95], v[152:155], v[200:203], v[92:95]
	v_mfma_f32_16x16x32_bf16 v[88:91], v[160:163], v[200:203], v[88:91]
	v_mfma_f32_16x16x32_bf16 v[76:79], v[152:155], v[208:211], v[76:79]
	v_mfma_f32_16x16x32_bf16 v[72:75], v[160:163], v[208:211], v[72:75]
	v_mfma_f32_16x16x32_bf16 v[120:123], v[156:159], v[188:191], v[120:123]
	v_mfma_f32_16x16x32_bf16 v[124:127], v[164:167], v[188:191], v[124:127]
	v_mfma_f32_16x16x32_bf16 v[108:111], v[156:159], v[196:199], v[108:111]
	v_mfma_f32_16x16x32_bf16 v[104:107], v[164:167], v[196:199], v[104:107]
	v_mfma_f32_16x16x32_bf16 v[92:95], v[156:159], v[204:207], v[92:95]
	v_mfma_f32_16x16x32_bf16 v[88:91], v[164:167], v[204:207], v[88:91]
	v_mfma_f32_16x16x32_bf16 v[76:79], v[156:159], v[212:215], v[76:79]
	v_mfma_f32_16x16x32_bf16 v[72:75], v[164:167], v[212:215], v[72:75]
	s_setprio 0
	s_setprio 1
	v_mfma_f32_16x16x32_bf16 v[116:119], v[168:171], v[184:187], v[116:119]
	v_mfma_f32_16x16x32_bf16 v[112:115], v[176:179], v[184:187], v[112:115]
	v_mfma_f32_16x16x32_bf16 v[100:103], v[168:171], v[192:195], v[100:103]
	v_mfma_f32_16x16x32_bf16 v[96:99], v[176:179], v[192:195], v[96:99]
	v_mfma_f32_16x16x32_bf16 v[84:87], v[168:171], v[200:203], v[84:87]
	v_mfma_f32_16x16x32_bf16 v[80:83], v[176:179], v[200:203], v[80:83]
	v_mfma_f32_16x16x32_bf16 v[68:71], v[168:171], v[208:211], v[68:71]
	v_mfma_f32_16x16x32_bf16 v[64:67], v[176:179], v[208:211], v[64:67]
	v_mfma_f32_16x16x32_bf16 v[116:119], v[172:175], v[188:191], v[116:119]
	v_mfma_f32_16x16x32_bf16 v[112:115], v[180:183], v[188:191], v[112:115]
	v_mfma_f32_16x16x32_bf16 v[100:103], v[172:175], v[196:199], v[100:103]
	v_mfma_f32_16x16x32_bf16 v[96:99], v[180:183], v[196:199], v[96:99]
	v_mfma_f32_16x16x32_bf16 v[84:87], v[172:175], v[204:207], v[84:87]
	v_mfma_f32_16x16x32_bf16 v[80:83], v[180:183], v[204:207], v[80:83]
	v_mfma_f32_16x16x32_bf16 v[68:71], v[172:175], v[212:215], v[68:71]
	v_mfma_f32_16x16x32_bf16 v[64:67], v[180:183], v[212:215], v[64:67]
	s_setprio 0
	s_barrier
	s_add_i32 s85, s67, s24
	v_lshl_add_u64 v[144:145], s[86:87], 0, v[132:133]
	s_mov_b32 m0, s85
	ds_read_b128 v[184:187], v151 offset:16384
	ds_read_b128 v[188:191], v151 offset:17408
	ds_read_b128 v[192:195], v151 offset:18432
	ds_read_b128 v[196:199], v151 offset:19456
	ds_read_b128 v[200:203], v151 offset:20480
	ds_read_b128 v[204:207], v151 offset:21504
	ds_read_b128 v[208:211], v151 offset:22528
	ds_read_b128 v[212:215], v151 offset:23552
	global_load_lds_dwordx4 v[144:145], off
	s_add_i32 m0, s85, 0x2000
	v_lshl_add_u64 v[216:217], s[86:87], 0, v[128:129]
	s_add_u32 s86, s86, s34
	s_addc_u32 s87, s87, s35
	s_add_i32 s85, s68, s24
	global_load_lds_dwordx4 v[216:217], off
	v_lshl_add_u64 v[218:219], s[86:87], 0, v[132:133]
	s_mov_b32 m0, s85
	v_lshl_add_u64 v[220:221], s[86:87], 0, v[128:129]
	global_load_lds_dwordx4 v[218:219], off
	s_add_i32 m0, s85, 0x2000
	v_lshl_add_u64 v[222:223], s[62:63], 0, v[134:135]
	global_load_lds_dwordx4 v[220:221], off
	s_mov_b32 m0, s25
	v_lshl_add_u64 v[224:225], s[62:63], 0, v[130:131]
	global_load_lds_dwordx4 v[222:223], off
	s_mov_b32 m0, s26
	s_nop 0
	global_load_lds_dwordx4 v[224:225], off
	s_waitcnt vmcnt(24)
	s_waitcnt lgkmcnt(0)
	s_barrier
	s_setprio 1
	s_waitcnt lgkmcnt(0)
	v_mfma_f32_16x16x32_bf16 v[60:63], v[152:155], v[184:187], v[60:63]
	v_mfma_f32_16x16x32_bf16 v[56:59], v[160:163], v[184:187], v[56:59]
	v_mfma_f32_16x16x32_bf16 v[44:47], v[152:155], v[192:195], v[44:47]
	v_mfma_f32_16x16x32_bf16 v[40:43], v[160:163], v[192:195], v[40:43]
	v_mfma_f32_16x16x32_bf16 v[28:31], v[152:155], v[200:203], v[28:31]
	v_mfma_f32_16x16x32_bf16 v[24:27], v[160:163], v[200:203], v[24:27]
	v_mfma_f32_16x16x32_bf16 v[12:15], v[152:155], v[208:211], v[12:15]
	v_mfma_f32_16x16x32_bf16 v[8:11], v[160:163], v[208:211], v[8:11]
	v_mfma_f32_16x16x32_bf16 v[60:63], v[156:159], v[188:191], v[60:63]
	v_mfma_f32_16x16x32_bf16 v[56:59], v[164:167], v[188:191], v[56:59]
	v_mfma_f32_16x16x32_bf16 v[44:47], v[156:159], v[196:199], v[44:47]
	v_mfma_f32_16x16x32_bf16 v[40:43], v[164:167], v[196:199], v[40:43]
	v_mfma_f32_16x16x32_bf16 v[28:31], v[156:159], v[204:207], v[28:31]
	v_mfma_f32_16x16x32_bf16 v[24:27], v[164:167], v[204:207], v[24:27]
	v_mfma_f32_16x16x32_bf16 v[12:15], v[156:159], v[212:215], v[12:15]
	v_mfma_f32_16x16x32_bf16 v[8:11], v[164:167], v[212:215], v[8:11]
	s_setprio 0
	s_setprio 1
	v_mfma_f32_16x16x32_bf16 v[52:55], v[168:171], v[184:187], v[52:55]
	v_mfma_f32_16x16x32_bf16 v[48:51], v[176:179], v[184:187], v[48:51]
	v_mfma_f32_16x16x32_bf16 v[36:39], v[168:171], v[192:195], v[36:39]
	v_mfma_f32_16x16x32_bf16 v[32:35], v[176:179], v[192:195], v[32:35]
	v_mfma_f32_16x16x32_bf16 v[20:23], v[168:171], v[200:203], v[20:23]
	v_mfma_f32_16x16x32_bf16 v[16:19], v[176:179], v[200:203], v[16:19]
	v_mfma_f32_16x16x32_bf16 v[4:7], v[168:171], v[208:211], v[4:7]
	v_mfma_f32_16x16x32_bf16 v[0:3], v[176:179], v[208:211], v[0:3]
	v_mfma_f32_16x16x32_bf16 v[52:55], v[172:175], v[188:191], v[52:55]
	v_mfma_f32_16x16x32_bf16 v[48:51], v[180:183], v[188:191], v[48:51]
	v_mfma_f32_16x16x32_bf16 v[36:39], v[172:175], v[196:199], v[36:39]
	v_mfma_f32_16x16x32_bf16 v[32:35], v[180:183], v[196:199], v[32:35]
	v_mfma_f32_16x16x32_bf16 v[20:23], v[172:175], v[204:207], v[20:23]
	v_mfma_f32_16x16x32_bf16 v[16:19], v[180:183], v[204:207], v[16:19]
	v_mfma_f32_16x16x32_bf16 v[4:7], v[172:175], v[212:215], v[4:7]
	v_mfma_f32_16x16x32_bf16 v[0:3], v[180:183], v[212:215], v[0:3]
	s_setprio 0
	s_barrier
	s_add_i32 s85, 0, 0x18000
	s_add_i32 s86, 0, 0x1c000
	v_add_u32_e32 v164, s85, v147
	v_add_u32_e32 v180, s86, v147
	ds_read_b128 v[152:155], v164
	ds_read_b128 v[156:159], v164 offset:1024
	ds_read_b128 v[160:163], v164 offset:2048
	ds_read_b128 v[164:167], v164 offset:3072
	ds_read_b128 v[168:171], v180
	ds_read_b128 v[172:175], v180 offset:1024
	ds_read_b128 v[176:179], v180 offset:2048
	ds_read_b128 v[180:183], v180 offset:3072
	s_add_u32 s62, s62, s34
	s_addc_u32 s63, s63, s35
	s_mov_b32 m0, s27
	v_lshl_add_u64 v[226:227], s[62:63], 0, v[134:135]
	ds_read_b128 v[184:187], v151 offset:32768
	ds_read_b128 v[188:191], v151 offset:33792
	ds_read_b128 v[192:195], v151 offset:34816
	ds_read_b128 v[196:199], v151 offset:35840
	ds_read_b128 v[200:203], v151 offset:36864
	ds_read_b128 v[204:207], v151 offset:37888
	ds_read_b128 v[208:211], v151 offset:38912
	ds_read_b128 v[212:215], v151 offset:39936
	global_load_lds_dwordx4 v[226:227], off
	v_lshl_add_u64 v[226:227], s[62:63], 0, v[130:131]
	s_mov_b32 m0, s28
	s_nop 0
	global_load_lds_dwordx4 v[226:227], off
	s_waitcnt vmcnt(8)
	s_waitcnt lgkmcnt(0)
	s_barrier
	s_setprio 1
	s_waitcnt lgkmcnt(0)
	v_mfma_f32_16x16x32_bf16 v[120:123], v[152:155], v[184:187], v[120:123]
	v_mfma_f32_16x16x32_bf16 v[124:127], v[160:163], v[184:187], v[124:127]
	v_mfma_f32_16x16x32_bf16 v[108:111], v[152:155], v[192:195], v[108:111]
	v_mfma_f32_16x16x32_bf16 v[104:107], v[160:163], v[192:195], v[104:107]
	v_mfma_f32_16x16x32_bf16 v[92:95], v[152:155], v[200:203], v[92:95]
	v_mfma_f32_16x16x32_bf16 v[88:91], v[160:163], v[200:203], v[88:91]
	v_mfma_f32_16x16x32_bf16 v[76:79], v[152:155], v[208:211], v[76:79]
	v_mfma_f32_16x16x32_bf16 v[72:75], v[160:163], v[208:211], v[72:75]
	v_mfma_f32_16x16x32_bf16 v[120:123], v[156:159], v[188:191], v[120:123]
	v_mfma_f32_16x16x32_bf16 v[124:127], v[164:167], v[188:191], v[124:127]
	v_mfma_f32_16x16x32_bf16 v[108:111], v[156:159], v[196:199], v[108:111]
	v_mfma_f32_16x16x32_bf16 v[104:107], v[164:167], v[196:199], v[104:107]
	v_mfma_f32_16x16x32_bf16 v[92:95], v[156:159], v[204:207], v[92:95]
	v_mfma_f32_16x16x32_bf16 v[88:91], v[164:167], v[204:207], v[88:91]
	v_mfma_f32_16x16x32_bf16 v[76:79], v[156:159], v[212:215], v[76:79]
	v_mfma_f32_16x16x32_bf16 v[72:75], v[164:167], v[212:215], v[72:75]
	s_setprio 0
	s_setprio 1
	v_mfma_f32_16x16x32_bf16 v[116:119], v[168:171], v[184:187], v[116:119]
	v_mfma_f32_16x16x32_bf16 v[112:115], v[176:179], v[184:187], v[112:115]
	v_mfma_f32_16x16x32_bf16 v[100:103], v[168:171], v[192:195], v[100:103]
	v_mfma_f32_16x16x32_bf16 v[96:99], v[176:179], v[192:195], v[96:99]
	v_mfma_f32_16x16x32_bf16 v[84:87], v[168:171], v[200:203], v[84:87]
	v_mfma_f32_16x16x32_bf16 v[80:83], v[176:179], v[200:203], v[80:83]
	v_mfma_f32_16x16x32_bf16 v[68:71], v[168:171], v[208:211], v[68:71]
	v_mfma_f32_16x16x32_bf16 v[64:67], v[176:179], v[208:211], v[64:67]
	v_mfma_f32_16x16x32_bf16 v[116:119], v[172:175], v[188:191], v[116:119]
	v_mfma_f32_16x16x32_bf16 v[112:115], v[180:183], v[188:191], v[112:115]
	v_mfma_f32_16x16x32_bf16 v[100:103], v[172:175], v[196:199], v[100:103]
	v_mfma_f32_16x16x32_bf16 v[96:99], v[180:183], v[196:199], v[96:99]
	v_mfma_f32_16x16x32_bf16 v[84:87], v[172:175], v[204:207], v[84:87]
	v_mfma_f32_16x16x32_bf16 v[80:83], v[180:183], v[204:207], v[80:83]
	v_mfma_f32_16x16x32_bf16 v[68:71], v[172:175], v[212:215], v[68:71]
	v_mfma_f32_16x16x32_bf16 v[64:67], v[180:183], v[212:215], v[64:67]
	s_setprio 0
	s_barrier
	s_add_i32 s62, s85, s24
	v_lshl_add_u64 v[144:145], v[144:145], 0, s[44:45]
	s_mov_b32 m0, s62
	ds_read_b128 v[184:187], v151 offset:49152
	ds_read_b128 v[188:191], v151 offset:50176
	ds_read_b128 v[192:195], v151 offset:51200
	ds_read_b128 v[196:199], v151 offset:52224
	ds_read_b128 v[200:203], v151 offset:53248
	ds_read_b128 v[204:207], v151 offset:54272
	ds_read_b128 v[208:211], v151 offset:55296
	ds_read_b128 v[212:215], v151 offset:56320
	global_load_lds_dwordx4 v[144:145], off
	v_lshl_add_u64 v[144:145], v[216:217], 0, s[44:45]
	s_add_i32 m0, s62, 0x2000
	s_add_i32 s62, s86, s24
	global_load_lds_dwordx4 v[144:145], off
	v_lshl_add_u64 v[144:145], v[218:219], 0, s[44:45]
	s_mov_b32 m0, s62
	s_nop 0
	global_load_lds_dwordx4 v[144:145], off
	v_lshl_add_u64 v[144:145], v[220:221], 0, s[44:45]
	s_add_i32 m0, s62, 0x2000
	s_nop 0
	global_load_lds_dwordx4 v[144:145], off
	v_lshl_add_u64 v[144:145], v[222:223], 0, s[44:45]
	s_mov_b32 m0, s30
	s_nop 0
	global_load_lds_dwordx4 v[144:145], off
	v_lshl_add_u64 v[144:145], v[224:225], 0, s[44:45]
	s_mov_b32 m0, s31
	s_nop 0
	global_load_lds_dwordx4 v[144:145], off
	s_waitcnt vmcnt(8)
	s_waitcnt lgkmcnt(0)
	s_barrier
	s_setprio 1
	s_waitcnt lgkmcnt(0)
	v_mfma_f32_16x16x32_bf16 v[60:63], v[152:155], v[184:187], v[60:63]
	v_mfma_f32_16x16x32_bf16 v[56:59], v[160:163], v[184:187], v[56:59]
	v_mfma_f32_16x16x32_bf16 v[44:47], v[152:155], v[192:195], v[44:47]
	v_mfma_f32_16x16x32_bf16 v[40:43], v[160:163], v[192:195], v[40:43]
	v_mfma_f32_16x16x32_bf16 v[28:31], v[152:155], v[200:203], v[28:31]
	v_mfma_f32_16x16x32_bf16 v[24:27], v[160:163], v[200:203], v[24:27]
	v_mfma_f32_16x16x32_bf16 v[12:15], v[152:155], v[208:211], v[12:15]
	v_mfma_f32_16x16x32_bf16 v[8:11], v[160:163], v[208:211], v[8:11]
	v_mfma_f32_16x16x32_bf16 v[60:63], v[156:159], v[188:191], v[60:63]
	v_mfma_f32_16x16x32_bf16 v[56:59], v[164:167], v[188:191], v[56:59]
	v_mfma_f32_16x16x32_bf16 v[44:47], v[156:159], v[196:199], v[44:47]
	v_mfma_f32_16x16x32_bf16 v[40:43], v[164:167], v[196:199], v[40:43]
	v_mfma_f32_16x16x32_bf16 v[28:31], v[156:159], v[204:207], v[28:31]
	v_mfma_f32_16x16x32_bf16 v[24:27], v[164:167], v[204:207], v[24:27]
	v_mfma_f32_16x16x32_bf16 v[12:15], v[156:159], v[212:215], v[12:15]
	v_mfma_f32_16x16x32_bf16 v[8:11], v[164:167], v[212:215], v[8:11]
	s_setprio 0
	s_setprio 1
	v_mfma_f32_16x16x32_bf16 v[52:55], v[168:171], v[184:187], v[52:55]
	v_mfma_f32_16x16x32_bf16 v[48:51], v[176:179], v[184:187], v[48:51]
	v_mfma_f32_16x16x32_bf16 v[36:39], v[168:171], v[192:195], v[36:39]
	v_mfma_f32_16x16x32_bf16 v[32:35], v[176:179], v[192:195], v[32:35]
	v_mfma_f32_16x16x32_bf16 v[20:23], v[168:171], v[200:203], v[20:23]
	v_mfma_f32_16x16x32_bf16 v[16:19], v[176:179], v[200:203], v[16:19]
	v_mfma_f32_16x16x32_bf16 v[4:7], v[168:171], v[208:211], v[4:7]
	v_mfma_f32_16x16x32_bf16 v[0:3], v[176:179], v[208:211], v[0:3]
	v_mfma_f32_16x16x32_bf16 v[52:55], v[172:175], v[188:191], v[52:55]
	v_mfma_f32_16x16x32_bf16 v[48:51], v[180:183], v[188:191], v[48:51]
	v_mfma_f32_16x16x32_bf16 v[36:39], v[172:175], v[196:199], v[36:39]
	v_mfma_f32_16x16x32_bf16 v[32:35], v[180:183], v[196:199], v[32:35]
	v_mfma_f32_16x16x32_bf16 v[20:23], v[172:175], v[204:207], v[20:23]
	v_mfma_f32_16x16x32_bf16 v[16:19], v[180:183], v[204:207], v[16:19]
	v_mfma_f32_16x16x32_bf16 v[4:7], v[172:175], v[212:215], v[4:7]
	v_mfma_f32_16x16x32_bf16 v[0:3], v[180:183], v[212:215], v[0:3]
	s_setprio 0
	s_barrier
	s_add_u32 s60, s60, 0x100
	s_addc_u32 s61, s61, 0
	s_add_u32 s82, s82, 0x100
	s_addc_u32 s83, s83, 0
	s_cmp_ge_i32 s84, s64
	s_mov_b32 s62, s84
	s_cbranch_scc1 .LBB0_857
